# kind-10 GEMM: transposed MFMA operands + register epilogue (cvt_pk, permlane16_swap, no LDS staging)
# speedup vs baseline: 1.0054x; 1.0054x over previous
; #define SCHED __builtin_amdgcn_sched_barrier(0)
; template <int EPI>
; __device__ __forceinline__ void gemm_tile(const GemmArgs& g, int brow, int bcol, int parity, bool first, bool nvalid, int nbrow, int nbcol) {
;     ...
;   int rowb_ = brow + wr * 64 + fq * 4; asm volatile("" : "+v"(rowb_));
;   int colb_ = bcol + wc * 32 + fr; asm volatile("" : "+v"(colb_));
;   float* W = (float*)(smem + ((wid < 3) ? (32768 + wid * 9216) : (98304 + (wid - 3) * 9216)));
;   const int wrow0 = rowb_ - fq * 4;
;   const int wcol0 = colb_ - fr;
;   const int lrow0 = wrow0 - brow;
;     ...
;   if constexpr (EPI == EPI_PLAIN) {
;     _Pragma("unroll") for (int ai = 0; ai < 2; ++ai) _Pragma("unroll") for (int bj = 0; bj < 2; ++bj) {
;       SCHED;
;       _Pragma("unroll") for (int m = 0; m < 4; ++m) _Pragma("unroll") for (int j = 0; j < 4; ++j) {
;         const float rs = rstd_s[lrow0 + ai * HALF + m * 16 + fq * 4 + j];
;         _Pragma("unroll") for (int n = 0; n < 2; ++n) W_WRITE(m, n, j, acc[ai][bj][m][n][j] * rs);
;       }
;       bfu* dst = g.outb + (long)(wrow0 + ai * HALF) * g.ldo + g.ocol0 + wcol0 + bj * HALF;
;       W_STORE_BF16(dst, g.ldo);
.LBB0_76:
	v_mbcnt_lo_u32_b32 v130, -1, 0
	v_mbcnt_hi_u32_b32 v130, -1, v130
	s_add_i32 s24, s24, 1
	s_and_b32 s2, s33, 0x100
	s_add_i32 s2, s2, s18
	v_and_b32_e32 v131, 15, v130
	v_lshrrev_b32_e32 v132, 4, v130
	v_lshl_add_u32 v133, v131, 2, s2
	ds_read_b32 v138, v133
	ds_read_b32 v139, v133 offset:64
	ds_read_b32 v140, v133 offset:128
	ds_read_b32 v141, v133 offset:192
	ds_read_b32 v142, v133 offset:512
	ds_read_b32 v143, v133 offset:576
	ds_read_b32 v144, v133 offset:640
	ds_read_b32 v145, v133 offset:704
	v_lshlrev_b32_e32 v134, 4, v132
	v_lshlrev_b32_e32 v135, 2, v132
	v_and_b32_e32 v134, 16, v134
	v_and_b32_e32 v135, 8, v135
	s_and_b32 s3, s34, 0x7fffff8
	s_lshl_b32 s3, s3, 5
	s_lshr_b32 s12, s33, 1
	s_and_b32 s12, s12, 0x60
	s_add_i32 s3, s3, s12
	v_or_b32_e32 v134, v134, v135
	v_add_lshl_u32 v134, v134, s3, 1
	v_mov_b32_e32 v135, 0
	s_lshr_b32 s12, s33, 2
	s_and_b32 s12, s12, 64
	s_add_i32 s12, s12, s38
	v_add_u32_e32 v136, s12, v131
	v_mad_u64_u32 v[134:135], vcc, v136, s89, v[134:135]
	v_lshl_add_u64 v[134:135], v[134:135], 0, s[16:17]
	s_mov_b64 s[12:13], 0x24000
	s_mov_b64 s[14:15], 0xb4000
	s_waitcnt lgkmcnt(0)
	v_pk_mul_f32 v[122:123], v[122:123], v[138:139] op_sel_hi:[1,0]
	v_pk_mul_f32 v[124:125], v[124:125], v[138:139] op_sel_hi:[1,0]
	v_pk_mul_f32 v[126:127], v[126:127], v[138:139] op_sel_hi:[1,0]
	v_pk_mul_f32 v[128:129], v[128:129], v[138:139] op_sel_hi:[1,0]
	v_pk_mul_f32 v[90:91], v[90:91], v[138:139] op_sel_hi:[1,0]
	v_pk_mul_f32 v[92:93], v[92:93], v[138:139] op_sel_hi:[1,0]
	v_pk_mul_f32 v[94:95], v[94:95], v[138:139] op_sel_hi:[1,0]
	v_pk_mul_f32 v[96:97], v[96:97], v[138:139] op_sel_hi:[1,0]
	v_cvt_pk_bf16_f32 v146, v122, v123
	v_cvt_pk_bf16_f32 v147, v124, v125
	v_cvt_pk_bf16_f32 v148, v126, v127
	v_cvt_pk_bf16_f32 v149, v128, v129
	v_cvt_pk_bf16_f32 v150, v90, v91
	v_cvt_pk_bf16_f32 v151, v92, v93
	v_cvt_pk_bf16_f32 v152, v94, v95
	v_cvt_pk_bf16_f32 v153, v96, v97
	v_permlane16_swap_b32_e32 v146, v148
	v_permlane16_swap_b32_e32 v147, v149
	v_permlane16_swap_b32_e32 v150, v152
	v_permlane16_swap_b32_e32 v151, v153
	global_store_dwordx4 v[134:135], v[146:149], off offset:3072
	global_store_dwordx4 v[134:135], v[150:153], off offset:3328
	v_lshl_add_u64 v[134:135], v[134:135], 0, s[12:13]
	v_pk_mul_f32 v[114:115], v[114:115], v[138:139] op_sel:[0,1] op_sel_hi:[1,1]
	v_pk_mul_f32 v[116:117], v[116:117], v[138:139] op_sel:[0,1] op_sel_hi:[1,1]
	v_pk_mul_f32 v[118:119], v[118:119], v[138:139] op_sel:[0,1] op_sel_hi:[1,1]
	v_pk_mul_f32 v[120:121], v[120:121], v[138:139] op_sel:[0,1] op_sel_hi:[1,1]
	v_pk_mul_f32 v[82:83], v[82:83], v[138:139] op_sel:[0,1] op_sel_hi:[1,1]
	v_pk_mul_f32 v[84:85], v[84:85], v[138:139] op_sel:[0,1] op_sel_hi:[1,1]
	v_pk_mul_f32 v[86:87], v[86:87], v[138:139] op_sel:[0,1] op_sel_hi:[1,1]
	v_pk_mul_f32 v[88:89], v[88:89], v[138:139] op_sel:[0,1] op_sel_hi:[1,1]
	v_cvt_pk_bf16_f32 v154, v114, v115
	v_cvt_pk_bf16_f32 v155, v116, v117
	v_cvt_pk_bf16_f32 v156, v118, v119
	v_cvt_pk_bf16_f32 v157, v120, v121
	v_cvt_pk_bf16_f32 v158, v82, v83
	v_cvt_pk_bf16_f32 v159, v84, v85
	v_cvt_pk_bf16_f32 v160, v86, v87
	v_cvt_pk_bf16_f32 v161, v88, v89
	v_permlane16_swap_b32_e32 v154, v156
	v_permlane16_swap_b32_e32 v155, v157
	v_permlane16_swap_b32_e32 v158, v160
	v_permlane16_swap_b32_e32 v159, v161
	global_store_dwordx4 v[134:135], v[154:157], off offset:3072
	global_store_dwordx4 v[134:135], v[158:161], off offset:3328
	v_lshl_add_u64 v[134:135], v[134:135], 0, s[12:13]
	v_pk_mul_f32 v[106:107], v[106:107], v[140:141] op_sel_hi:[1,0]
	v_pk_mul_f32 v[108:109], v[108:109], v[140:141] op_sel_hi:[1,0]
	v_pk_mul_f32 v[110:111], v[110:111], v[140:141] op_sel_hi:[1,0]
	v_pk_mul_f32 v[112:113], v[112:113], v[140:141] op_sel_hi:[1,0]
	v_pk_mul_f32 v[74:75], v[74:75], v[140:141] op_sel_hi:[1,0]
	v_pk_mul_f32 v[76:77], v[76:77], v[140:141] op_sel_hi:[1,0]
	v_pk_mul_f32 v[78:79], v[78:79], v[140:141] op_sel_hi:[1,0]
	v_pk_mul_f32 v[80:81], v[80:81], v[140:141] op_sel_hi:[1,0]
	v_cvt_pk_bf16_f32 v146, v106, v107
	v_cvt_pk_bf16_f32 v147, v108, v109
	v_cvt_pk_bf16_f32 v148, v110, v111
	v_cvt_pk_bf16_f32 v149, v112, v113
	v_cvt_pk_bf16_f32 v150, v74, v75
	v_cvt_pk_bf16_f32 v151, v76, v77
	v_cvt_pk_bf16_f32 v152, v78, v79
	v_cvt_pk_bf16_f32 v153, v80, v81
	v_permlane16_swap_b32_e32 v146, v148
	v_permlane16_swap_b32_e32 v147, v149
	v_permlane16_swap_b32_e32 v150, v152
	v_permlane16_swap_b32_e32 v151, v153
	global_store_dwordx4 v[134:135], v[146:149], off offset:3072
	global_store_dwordx4 v[134:135], v[150:153], off offset:3328
	v_lshl_add_u64 v[134:135], v[134:135], 0, s[12:13]
	v_pk_mul_f32 v[98:99], v[98:99], v[140:141] op_sel:[0,1] op_sel_hi:[1,1]
	v_pk_mul_f32 v[100:101], v[100:101], v[140:141] op_sel:[0,1] op_sel_hi:[1,1]
	v_pk_mul_f32 v[102:103], v[102:103], v[140:141] op_sel:[0,1] op_sel_hi:[1,1]
	v_pk_mul_f32 v[104:105], v[104:105], v[140:141] op_sel:[0,1] op_sel_hi:[1,1]
	v_pk_mul_f32 v[66:67], v[66:67], v[140:141] op_sel:[0,1] op_sel_hi:[1,1]
	v_pk_mul_f32 v[68:69], v[68:69], v[140:141] op_sel:[0,1] op_sel_hi:[1,1]
	v_pk_mul_f32 v[70:71], v[70:71], v[140:141] op_sel:[0,1] op_sel_hi:[1,1]
	v_pk_mul_f32 v[72:73], v[72:73], v[140:141] op_sel:[0,1] op_sel_hi:[1,1]
; #define SCHED __builtin_amdgcn_sched_barrier(0)
; template <int EPI>
; __device__ __forceinline__ void gemm_tile(const GemmArgs& g, int brow, int bcol, int parity, bool first, bool nvalid, int nbrow, int nbcol) {
;     ...
;     _Pragma("unroll") for (int ai = 0; ai < 2; ++ai) _Pragma("unroll") for (int bj = 0; bj < 2; ++bj) {
;       SCHED;
;       _Pragma("unroll") for (int m = 0; m < 4; ++m) _Pragma("unroll") for (int j = 0; j < 4; ++j) {
;         const float rs = rstd_s[lrow0 + ai * HALF + m * 16 + fq * 4 + j];
;         _Pragma("unroll") for (int n = 0; n < 2; ++n) W_WRITE(m, n, j, acc[ai][bj][m][n][j] * rs);
;       }
;       bfu* dst = g.outb + (long)(wrow0 + ai * HALF) * g.ldo + g.ocol0 + wcol0 + bj * HALF;
;       W_STORE_BF16(dst, g.ldo);
;     }
	v_cvt_pk_bf16_f32 v154, v98, v99
	v_cvt_pk_bf16_f32 v155, v100, v101
	v_cvt_pk_bf16_f32 v156, v102, v103
	v_cvt_pk_bf16_f32 v157, v104, v105
	v_cvt_pk_bf16_f32 v158, v66, v67
	v_cvt_pk_bf16_f32 v159, v68, v69
	v_cvt_pk_bf16_f32 v160, v70, v71
	v_cvt_pk_bf16_f32 v161, v72, v73
	v_permlane16_swap_b32_e32 v154, v156
	v_permlane16_swap_b32_e32 v155, v157
	v_permlane16_swap_b32_e32 v158, v160
	v_permlane16_swap_b32_e32 v159, v161
	global_store_dwordx4 v[134:135], v[154:157], off offset:3072
	global_store_dwordx4 v[134:135], v[158:161], off offset:3328
	v_lshl_add_u64 v[134:135], v[134:135], 0, s[14:15]
	v_pk_mul_f32 v[58:59], v[58:59], v[142:143] op_sel_hi:[1,0]
	v_pk_mul_f32 v[60:61], v[60:61], v[142:143] op_sel_hi:[1,0]
	v_pk_mul_f32 v[62:63], v[62:63], v[142:143] op_sel_hi:[1,0]
	v_pk_mul_f32 v[64:65], v[64:65], v[142:143] op_sel_hi:[1,0]
	v_pk_mul_f32 v[26:27], v[26:27], v[142:143] op_sel_hi:[1,0]
	v_pk_mul_f32 v[28:29], v[28:29], v[142:143] op_sel_hi:[1,0]
	v_pk_mul_f32 v[30:31], v[30:31], v[142:143] op_sel_hi:[1,0]
	v_pk_mul_f32 v[32:33], v[32:33], v[142:143] op_sel_hi:[1,0]
	v_cvt_pk_bf16_f32 v146, v58, v59
	v_cvt_pk_bf16_f32 v147, v60, v61
	v_cvt_pk_bf16_f32 v148, v62, v63
	v_cvt_pk_bf16_f32 v149, v64, v65
	v_cvt_pk_bf16_f32 v150, v26, v27
	v_cvt_pk_bf16_f32 v151, v28, v29
	v_cvt_pk_bf16_f32 v152, v30, v31
	v_cvt_pk_bf16_f32 v153, v32, v33
	v_permlane16_swap_b32_e32 v146, v148
	v_permlane16_swap_b32_e32 v147, v149
	v_permlane16_swap_b32_e32 v150, v152
	v_permlane16_swap_b32_e32 v151, v153
	global_store_dwordx4 v[134:135], v[146:149], off offset:3072
	global_store_dwordx4 v[134:135], v[150:153], off offset:3328
	v_lshl_add_u64 v[134:135], v[134:135], 0, s[12:13]
	v_pk_mul_f32 v[50:51], v[50:51], v[142:143] op_sel:[0,1] op_sel_hi:[1,1]
	v_pk_mul_f32 v[52:53], v[52:53], v[142:143] op_sel:[0,1] op_sel_hi:[1,1]
	v_pk_mul_f32 v[54:55], v[54:55], v[142:143] op_sel:[0,1] op_sel_hi:[1,1]
	v_pk_mul_f32 v[56:57], v[56:57], v[142:143] op_sel:[0,1] op_sel_hi:[1,1]
	v_pk_mul_f32 v[18:19], v[18:19], v[142:143] op_sel:[0,1] op_sel_hi:[1,1]
	v_pk_mul_f32 v[20:21], v[20:21], v[142:143] op_sel:[0,1] op_sel_hi:[1,1]
	v_pk_mul_f32 v[22:23], v[22:23], v[142:143] op_sel:[0,1] op_sel_hi:[1,1]
	v_pk_mul_f32 v[24:25], v[24:25], v[142:143] op_sel:[0,1] op_sel_hi:[1,1]
	v_cvt_pk_bf16_f32 v154, v50, v51
	v_cvt_pk_bf16_f32 v155, v52, v53
	v_cvt_pk_bf16_f32 v156, v54, v55
	v_cvt_pk_bf16_f32 v157, v56, v57
	v_cvt_pk_bf16_f32 v158, v18, v19
	v_cvt_pk_bf16_f32 v159, v20, v21
	v_cvt_pk_bf16_f32 v160, v22, v23
	v_cvt_pk_bf16_f32 v161, v24, v25
	v_permlane16_swap_b32_e32 v154, v156
	v_permlane16_swap_b32_e32 v155, v157
	v_permlane16_swap_b32_e32 v158, v160
	v_permlane16_swap_b32_e32 v159, v161
	global_store_dwordx4 v[134:135], v[154:157], off offset:3072
	global_store_dwordx4 v[134:135], v[158:161], off offset:3328
	v_lshl_add_u64 v[134:135], v[134:135], 0, s[12:13]
	v_pk_mul_f32 v[42:43], v[42:43], v[144:145] op_sel_hi:[1,0]
	v_pk_mul_f32 v[44:45], v[44:45], v[144:145] op_sel_hi:[1,0]
	v_pk_mul_f32 v[46:47], v[46:47], v[144:145] op_sel_hi:[1,0]
	v_pk_mul_f32 v[48:49], v[48:49], v[144:145] op_sel_hi:[1,0]
	v_pk_mul_f32 v[10:11], v[10:11], v[144:145] op_sel_hi:[1,0]
	v_pk_mul_f32 v[12:13], v[12:13], v[144:145] op_sel_hi:[1,0]
	v_pk_mul_f32 v[14:15], v[14:15], v[144:145] op_sel_hi:[1,0]
	v_pk_mul_f32 v[16:17], v[16:17], v[144:145] op_sel_hi:[1,0]
	v_cvt_pk_bf16_f32 v146, v42, v43
	v_cvt_pk_bf16_f32 v147, v44, v45
	v_cvt_pk_bf16_f32 v148, v46, v47
	v_cvt_pk_bf16_f32 v149, v48, v49
	v_cvt_pk_bf16_f32 v150, v10, v11
	v_cvt_pk_bf16_f32 v151, v12, v13
	v_cvt_pk_bf16_f32 v152, v14, v15
	v_cvt_pk_bf16_f32 v153, v16, v17
	v_permlane16_swap_b32_e32 v146, v148
	v_permlane16_swap_b32_e32 v147, v149
	v_permlane16_swap_b32_e32 v150, v152
	v_permlane16_swap_b32_e32 v151, v153
	global_store_dwordx4 v[134:135], v[146:149], off offset:3072
	global_store_dwordx4 v[134:135], v[150:153], off offset:3328
	v_lshl_add_u64 v[134:135], v[134:135], 0, s[12:13]
	v_pk_mul_f32 v[34:35], v[34:35], v[144:145] op_sel:[0,1] op_sel_hi:[1,1]
	v_pk_mul_f32 v[36:37], v[36:37], v[144:145] op_sel:[0,1] op_sel_hi:[1,1]
	v_pk_mul_f32 v[38:39], v[38:39], v[144:145] op_sel:[0,1] op_sel_hi:[1,1]
	v_pk_mul_f32 v[40:41], v[40:41], v[144:145] op_sel:[0,1] op_sel_hi:[1,1]
	v_pk_mul_f32 v[2:3], v[2:3], v[144:145] op_sel:[0,1] op_sel_hi:[1,1]
	v_pk_mul_f32 v[4:5], v[4:5], v[144:145] op_sel:[0,1] op_sel_hi:[1,1]
	v_pk_mul_f32 v[6:7], v[6:7], v[144:145] op_sel:[0,1] op_sel_hi:[1,1]
	v_pk_mul_f32 v[8:9], v[8:9], v[144:145] op_sel:[0,1] op_sel_hi:[1,1]
	v_cvt_pk_bf16_f32 v154, v34, v35
	v_cvt_pk_bf16_f32 v155, v36, v37
	v_cvt_pk_bf16_f32 v156, v38, v39
	v_cvt_pk_bf16_f32 v157, v40, v41
	v_cvt_pk_bf16_f32 v158, v2, v3
	v_cvt_pk_bf16_f32 v159, v4, v5
	v_cvt_pk_bf16_f32 v160, v6, v7
	v_cvt_pk_bf16_f32 v161, v8, v9
	v_permlane16_swap_b32_e32 v154, v156
	v_permlane16_swap_b32_e32 v155, v157
	v_permlane16_swap_b32_e32 v158, v160
	v_permlane16_swap_b32_e32 v159, v161
	global_store_dwordx4 v[134:135], v[154:157], off offset:3072
	global_store_dwordx4 v[134:135], v[158:161], off offset:3328
	s_mov_b64 s[14:15], -1
	s_and_b64 vcc, exec, s[0:1]
	s_cbranch_vccnz .LBB0_95

; #define STAGE_B(P, br, kt) do { const char* _gb = (const char*)(Bt + ((long)(br) * K + (long)(kt) * BK)); \
;     __builtin_amdgcn_global_load_lds((const unsigned*)(_gb + bofl0), (unsigned*)((char*)(P) + gtid_ * 16), 16, 0, 0); \
;     __builtin_amdgcn_global_load_lds((const unsigned*)(_gb + (long)K * 128 + bofl0), (unsigned*)((char*)(P) + gtid_ * 16 + 8192), 16, 0, 0); } while (0)
; #define LDA(dst, b, h) for (int m = 0; m < 4; ++m) for (int k = 0; k < 2; ++k) \
;     dst[m][k] = *reinterpret_cast<const bf16x8*>((char*)SA(b, h) + lds_byte(wr * 64 + m * 16 + fr, k * 32 + fq * 8))
; #define LDB(dst, b, h) for (int n = 0; n < 2; ++n) for (int k = 0; k < 2; ++k) \
;     dst[n][k] = *reinterpret_cast<const bf16x8*>((char*)SB(b, h) + lds_byte(wc * 32 + n * 16 + fr, k * 32 + fq * 8))
; #define MMA(ai, bj, At_, Bt_) do { __builtin_amdgcn_s_setprio(1); \
;     for (int m = 0; m < 4; ++m) for (int n = 0; n < 2; ++n) for (int k = 0; k < 2; ++k) \
;       acc[ai][bj][m][n] = __builtin_amdgcn_mfma_f32_16x16x32_bf16(At_[m][k], Bt_[n][k], acc[ai][bj][m][n], 0, 0, 0); \
;     __builtin_amdgcn_s_setprio(0); } while (0)
; #define WAIT_V(n) asm volatile("s_waitcnt vmcnt(" #n ")" ::: "memory")
; #define WAIT_L(n) asm volatile("s_waitcnt lgkmcnt(" #n ")" ::: "memory")
; template <int EPI>
; __device__ __forceinline__ void gemm_tile(const GemmArgs& g, int brow, int bcol, int parity, bool first, bool nvalid, int nbrow, int nbcol) {
;     ...
;   for (int t = 0; t < nt - 2; t += 2) {
;     LDB(B0, 0, 0); SCHED; LDA(At, 0, 0); STAGE_A(SA(1, 1), brow + HALF, t + 1);
;     WAIT_L(8); BAR; WAIT_L(0); MMA(0, 0, At, B0); BAR; SCHED;
;     LDB(B1, 0, 1); STAGE_B(SB(0, 0), bcol, t + 2);
;     BAR; WAIT_L(0); MMA(0, 1, At, B1); BAR; SCHED;
;     LDA(At, 0, 1); STAGE_A(SA(0, 0), brow, t + 2);
;     BAR; WAIT_L(0); MMA(1, 0, At, B0); BAR; SCHED;
;     STAGE_B(SB(0, 1), bcol + HALF, t + 2);
;     WAIT_V(6); BAR; MMA(1, 1, At, B1); BAR; SCHED;
;     LDB(B0, 1, 0); SCHED; LDA(At, 1, 0); STAGE_A(SA(0, 1), brow + HALF, t + 2);
;     WAIT_L(8); BAR; WAIT_L(0); MMA(0, 0, At, B0); BAR; SCHED;
;     LDB(B1, 1, 1); STAGE_B(SB(1, 0), bcol, t + 3);
;     BAR; WAIT_L(0); MMA(0, 1, At, B1); BAR; SCHED;
;     LDA(At, 1, 1); STAGE_A(SA(1, 0), brow, t + 3);
;     BAR; WAIT_L(0); MMA(1, 0, At, B0); BAR; SCHED;
;     STAGE_B(SB(1, 1), bcol + HALF, t + 3);
;     WAIT_V(6); BAR; MMA(1, 1, At, B1); BAR; SCHED;
;   }
.LBB0_90:
	ds_read_b128 v[164:167], v157
	ds_read_b128 v[168:171], v157 offset:1024
	ds_read_b128 v[172:175], v157 offset:2048
	ds_read_b128 v[176:179], v157 offset:3072
	v_add_u32_e32 v161, 0xc000, v137
	v_lshl_add_u64 v[210:211], s[0:1], 0, v[130:131]
	v_readfirstlane_b32 s2, v161
	v_add_u32_e32 v162, 0xe000, v137
	v_lshl_add_u64 v[158:159], v[210:211], 0, s[26:27]
	s_mov_b32 m0, s2
	v_readfirstlane_b32 s2, v162
	ds_read_b128 v[180:183], v147
	ds_read_b128 v[184:187], v147 offset:1024
	ds_read_b128 v[188:191], v146
	ds_read_b128 v[192:195], v146 offset:1024
	ds_read_b128 v[196:199], v145
	ds_read_b128 v[202:205], v145 offset:1024
	ds_read_b128 v[206:209], v144
	ds_read_b128 v[216:219], v144 offset:1024
	global_load_lds_dwordx4 v[158:159], off
	v_lshl_add_u64 v[158:159], v[210:211], 0, s[36:37]
	s_mov_b32 m0, s2
	s_nop 0
	global_load_lds_dwordx4 v[158:159], off
	s_waitcnt lgkmcnt(8)
	s_barrier
	s_waitcnt lgkmcnt(0)
	s_setprio 1
	s_waitcnt lgkmcnt(0)
	v_mfma_f32_16x16x32_bf16 v[126:129], v[164:167], v[180:183], v[126:129]
	v_mfma_f32_16x16x32_bf16 v[122:125], v[172:175], v[180:183], v[122:125]
	v_mfma_f32_16x16x32_bf16 v[118:121], v[164:167], v[188:191], v[118:121]
	v_mfma_f32_16x16x32_bf16 v[114:117], v[172:175], v[188:191], v[114:117]
	v_mfma_f32_16x16x32_bf16 v[110:113], v[164:167], v[196:199], v[110:113]
	v_mfma_f32_16x16x32_bf16 v[106:109], v[172:175], v[196:199], v[106:109]
	v_mfma_f32_16x16x32_bf16 v[102:105], v[164:167], v[206:209], v[102:105]
	v_mfma_f32_16x16x32_bf16 v[98:101], v[172:175], v[206:209], v[98:101]
	v_mfma_f32_16x16x32_bf16 v[126:129], v[168:171], v[184:187], v[126:129]
	v_mfma_f32_16x16x32_bf16 v[122:125], v[176:179], v[184:187], v[122:125]
	v_mfma_f32_16x16x32_bf16 v[118:121], v[168:171], v[192:195], v[118:121]
	v_mfma_f32_16x16x32_bf16 v[114:117], v[176:179], v[192:195], v[114:117]
	v_mfma_f32_16x16x32_bf16 v[110:113], v[168:171], v[202:205], v[110:113]
	v_mfma_f32_16x16x32_bf16 v[106:109], v[176:179], v[202:205], v[106:109]
	v_mfma_f32_16x16x32_bf16 v[102:105], v[168:171], v[216:219], v[102:105]
	v_mfma_f32_16x16x32_bf16 v[98:101], v[176:179], v[216:219], v[98:101]
	s_setprio 0
	s_barrier
	v_lshl_add_u64 v[212:213], s[12:13], 0, v[130:131]
	s_mov_b64 s[2:3], 0x900100
	v_add_u32_e32 v158, s14, v142
	v_lshl_add_u64 v[222:223], v[212:213], 0, s[2:3]
	v_readfirstlane_b32 s2, v158
	s_mov_b32 m0, s2
	s_mov_b64 s[2:3], 0x920100
	v_add_u32_e32 v159, 0x2000, v158
	ds_read_b128 v[228:231], v154
	ds_read_b128 v[232:235], v154 offset:1024
	ds_read_b128 v[236:239], v154 offset:2048
	ds_read_b128 v[240:243], v154 offset:3072
	global_load_lds_dwordx4 v[222:223], off
	v_lshl_add_u64 v[222:223], v[212:213], 0, s[2:3]
	v_readfirstlane_b32 s2, v159
	s_mov_b32 m0, s2
	s_nop 0
	global_load_lds_dwordx4 v[222:223], off
	s_barrier
	s_waitcnt lgkmcnt(0)
	s_setprio 1
	s_waitcnt lgkmcnt(0)
	v_mfma_f32_16x16x32_bf16 v[94:97], v[228:231], v[180:183], v[94:97]
	v_mfma_f32_16x16x32_bf16 v[90:93], v[236:239], v[180:183], v[90:93]
	v_mfma_f32_16x16x32_bf16 v[86:89], v[228:231], v[188:191], v[86:89]
	v_mfma_f32_16x16x32_bf16 v[82:85], v[236:239], v[188:191], v[82:85]
	v_mfma_f32_16x16x32_bf16 v[78:81], v[228:231], v[196:199], v[78:81]
	v_mfma_f32_16x16x32_bf16 v[74:77], v[236:239], v[196:199], v[74:77]
	v_mfma_f32_16x16x32_bf16 v[70:73], v[228:231], v[206:209], v[70:73]
	v_mfma_f32_16x16x32_bf16 v[66:69], v[236:239], v[206:209], v[66:69]
	v_mfma_f32_16x16x32_bf16 v[94:97], v[232:235], v[184:187], v[94:97]
	v_mfma_f32_16x16x32_bf16 v[90:93], v[240:243], v[184:187], v[90:93]
	v_mfma_f32_16x16x32_bf16 v[86:89], v[232:235], v[192:195], v[86:89]
	v_mfma_f32_16x16x32_bf16 v[82:85], v[240:243], v[192:195], v[82:85]
	v_mfma_f32_16x16x32_bf16 v[78:81], v[232:235], v[202:205], v[78:81]
	v_mfma_f32_16x16x32_bf16 v[74:77], v[240:243], v[202:205], v[74:77]
	v_mfma_f32_16x16x32_bf16 v[70:73], v[232:235], v[216:219], v[70:73]
	v_mfma_f32_16x16x32_bf16 v[66:69], v[240:243], v[216:219], v[66:69]
	s_setprio 0
	s_barrier
	v_readfirstlane_b32 s2, v137
	v_lshl_add_u64 v[222:223], v[210:211], 0, s[40:41]
	s_mov_b32 m0, s2
	v_readfirstlane_b32 s2, v136
	ds_read_b128 v[180:183], v147 offset:16384
	ds_read_b128 v[184:187], v147 offset:17408
	ds_read_b128 v[188:191], v146 offset:16384
	ds_read_b128 v[192:195], v146 offset:17408
	ds_read_b128 v[196:199], v145 offset:16384
	ds_read_b128 v[202:205], v145 offset:17408
	ds_read_b128 v[206:209], v144 offset:16384
	ds_read_b128 v[216:219], v144 offset:17408
	global_load_lds_dwordx4 v[222:223], off
	v_lshl_add_u64 v[222:223], v[210:211], 0, s[44:45]
	s_mov_b32 m0, s2
	s_nop 0
	global_load_lds_dwordx4 v[222:223], off
	s_barrier
	s_waitcnt lgkmcnt(0)
	s_setprio 1
	s_waitcnt lgkmcnt(0)
	v_mfma_f32_16x16x32_bf16 v[62:65], v[164:167], v[180:183], v[62:65]
	v_mfma_f32_16x16x32_bf16 v[58:61], v[172:175], v[180:183], v[58:61]
	v_mfma_f32_16x16x32_bf16 v[54:57], v[164:167], v[188:191], v[54:57]
	v_mfma_f32_16x16x32_bf16 v[50:53], v[172:175], v[188:191], v[50:53]
	v_mfma_f32_16x16x32_bf16 v[46:49], v[164:167], v[196:199], v[46:49]
	v_mfma_f32_16x16x32_bf16 v[42:45], v[172:175], v[196:199], v[42:45]
	v_mfma_f32_16x16x32_bf16 v[38:41], v[164:167], v[206:209], v[38:41]
	v_mfma_f32_16x16x32_bf16 v[34:37], v[172:175], v[206:209], v[34:37]
	v_mfma_f32_16x16x32_bf16 v[62:65], v[168:171], v[184:187], v[62:65]
	v_mfma_f32_16x16x32_bf16 v[58:61], v[176:179], v[184:187], v[58:61]
	v_mfma_f32_16x16x32_bf16 v[54:57], v[168:171], v[192:195], v[54:57]
	v_mfma_f32_16x16x32_bf16 v[50:53], v[176:179], v[192:195], v[50:53]
	v_mfma_f32_16x16x32_bf16 v[46:49], v[168:171], v[202:205], v[46:49]
	v_mfma_f32_16x16x32_bf16 v[42:45], v[176:179], v[202:205], v[42:45]
	v_mfma_f32_16x16x32_bf16 v[38:41], v[168:171], v[216:219], v[38:41]
	v_mfma_f32_16x16x32_bf16 v[34:37], v[176:179], v[216:219], v[34:37]
	s_setprio 0
	s_barrier
; #define STAGE_B(P, br, kt) do { const char* _gb = (const char*)(Bt + ((long)(br) * K + (long)(kt) * BK)); \
;     __builtin_amdgcn_global_load_lds((const unsigned*)(_gb + bofl0), (unsigned*)((char*)(P) + gtid_ * 16), 16, 0, 0); \
;     __builtin_amdgcn_global_load_lds((const unsigned*)(_gb + (long)K * 128 + bofl0), (unsigned*)((char*)(P) + gtid_ * 16 + 8192), 16, 0, 0); } while (0)
; #define LDA(dst, b, h) for (int m = 0; m < 4; ++m) for (int k = 0; k < 2; ++k) \
;     dst[m][k] = *reinterpret_cast<const bf16x8*>((char*)SA(b, h) + lds_byte(wr * 64 + m * 16 + fr, k * 32 + fq * 8))
; #define LDB(dst, b, h) for (int n = 0; n < 2; ++n) for (int k = 0; k < 2; ++k) \
;     dst[n][k] = *reinterpret_cast<const bf16x8*>((char*)SB(b, h) + lds_byte(wc * 32 + n * 16 + fr, k * 32 + fq * 8))
; #define MMA(ai, bj, At_, Bt_) do { __builtin_amdgcn_s_setprio(1); \
;     for (int m = 0; m < 4; ++m) for (int n = 0; n < 2; ++n) for (int k = 0; k < 2; ++k) \
;       acc[ai][bj][m][n] = __builtin_amdgcn_mfma_f32_16x16x32_bf16(At_[m][k], Bt_[n][k], acc[ai][bj][m][n], 0, 0, 0); \
;     __builtin_amdgcn_s_setprio(0); } while (0)
; #define WAIT_V(n) asm volatile("s_waitcnt vmcnt(" #n ")" ::: "memory")
; #define WAIT_L(n) asm volatile("s_waitcnt lgkmcnt(" #n ")" ::: "memory")
; template <int EPI>
; __device__ __forceinline__ void gemm_tile(const GemmArgs& g, int brow, int bcol, int parity, bool first, bool nvalid, int nbrow, int nbcol) {
;     ...
;   for (int t = 0; t < nt - 2; t += 2) {
;     LDB(B0, 0, 0); SCHED; LDA(At, 0, 0); STAGE_A(SA(1, 1), brow + HALF, t + 1);
;     WAIT_L(8); BAR; WAIT_L(0); MMA(0, 0, At, B0); BAR; SCHED;
;     LDB(B1, 0, 1); STAGE_B(SB(0, 0), bcol, t + 2);
;     BAR; WAIT_L(0); MMA(0, 1, At, B1); BAR; SCHED;
;     LDA(At, 0, 1); STAGE_A(SA(0, 0), brow, t + 2);
;     BAR; WAIT_L(0); MMA(1, 0, At, B0); BAR; SCHED;
;     STAGE_B(SB(0, 1), bcol + HALF, t + 2);
;     WAIT_V(6); BAR; MMA(1, 1, At, B1); BAR; SCHED;
;     LDB(B0, 1, 0); SCHED; LDA(At, 1, 0); STAGE_A(SA(0, 1), brow + HALF, t + 2);
;     WAIT_L(8); BAR; WAIT_L(0); MMA(0, 0, At, B0); BAR; SCHED;
;     LDB(B1, 1, 1); STAGE_B(SB(1, 0), bcol, t + 3);
;     BAR; WAIT_L(0); MMA(0, 1, At, B1); BAR; SCHED;
;     LDA(At, 1, 1); STAGE_A(SA(1, 0), brow, t + 3);
;     BAR; WAIT_L(0); MMA(1, 0, At, B0); BAR; SCHED;
;     STAGE_B(SB(1, 1), bcol + HALF, t + 3);
;     WAIT_V(6); BAR; MMA(1, 1, At, B1); BAR; SCHED;
;   }
	s_mov_b64 s[2:3], 0x940100
	v_lshl_add_u64 v[164:165], v[212:213], 0, s[2:3]
	v_readfirstlane_b32 s2, v135
	s_mov_b32 m0, s2
	s_mov_b64 s[2:3], 0x960100
	v_add_u32_e32 v160, 0x2000, v135
	global_load_lds_dwordx4 v[164:165], off
	v_lshl_add_u64 v[164:165], v[212:213], 0, s[2:3]
	v_readfirstlane_b32 s2, v160
	s_mov_b32 m0, s2
	s_nop 0
	global_load_lds_dwordx4 v[164:165], off
	s_waitcnt vmcnt(6)
	s_barrier
	s_setprio 1
	v_mfma_f32_16x16x32_bf16 v[30:33], v[228:231], v[180:183], v[30:33]
	v_mfma_f32_16x16x32_bf16 v[26:29], v[236:239], v[180:183], v[26:29]
	v_mfma_f32_16x16x32_bf16 v[22:25], v[228:231], v[188:191], v[22:25]
	v_mfma_f32_16x16x32_bf16 v[18:21], v[236:239], v[188:191], v[18:21]
	v_mfma_f32_16x16x32_bf16 v[14:17], v[228:231], v[196:199], v[14:17]
	v_mfma_f32_16x16x32_bf16 v[10:13], v[236:239], v[196:199], v[10:13]
	v_mfma_f32_16x16x32_bf16 v[6:9], v[228:231], v[206:209], v[6:9]
	v_mfma_f32_16x16x32_bf16 v[2:5], v[236:239], v[206:209], v[2:5]
	v_mfma_f32_16x16x32_bf16 v[30:33], v[232:235], v[184:187], v[30:33]
	v_mfma_f32_16x16x32_bf16 v[26:29], v[240:243], v[184:187], v[26:29]
	v_mfma_f32_16x16x32_bf16 v[22:25], v[232:235], v[192:195], v[22:25]
	v_mfma_f32_16x16x32_bf16 v[18:21], v[240:243], v[192:195], v[18:21]
	v_mfma_f32_16x16x32_bf16 v[14:17], v[232:235], v[202:205], v[14:17]
	v_mfma_f32_16x16x32_bf16 v[10:13], v[240:243], v[202:205], v[10:13]
	v_mfma_f32_16x16x32_bf16 v[6:9], v[232:235], v[216:219], v[6:9]
	v_mfma_f32_16x16x32_bf16 v[2:5], v[240:243], v[216:219], v[2:5]
	s_setprio 0
	s_barrier
	ds_read_b128 v[164:167], v149
	ds_read_b128 v[168:171], v149 offset:1024
	ds_read_b128 v[172:175], v149 offset:2048
	ds_read_b128 v[176:179], v149 offset:3072
	v_readfirstlane_b32 s2, v134
	v_lshl_add_u64 v[222:223], v[210:211], 0, s[46:47]
	s_mov_b32 m0, s2
	v_readfirstlane_b32 s2, v133
	ds_read_b128 v[180:183], v147 offset:32768
	ds_read_b128 v[184:187], v147 offset:33792
	ds_read_b128 v[188:191], v146 offset:32768
	ds_read_b128 v[192:195], v146 offset:33792
	ds_read_b128 v[196:199], v145 offset:32768
	ds_read_b128 v[202:205], v145 offset:33792
	ds_read_b128 v[206:209], v144 offset:32768
	ds_read_b128 v[216:219], v144 offset:33792
	global_load_lds_dwordx4 v[222:223], off
	v_lshl_add_u64 v[222:223], v[210:211], 0, s[48:49]
	s_mov_b32 m0, s2
	s_nop 0
	global_load_lds_dwordx4 v[222:223], off
	s_waitcnt lgkmcnt(8)
	s_barrier
	s_waitcnt lgkmcnt(0)
	s_setprio 1
	s_waitcnt lgkmcnt(0)
	v_mfma_f32_16x16x32_bf16 v[126:129], v[164:167], v[180:183], v[126:129]
	v_mfma_f32_16x16x32_bf16 v[122:125], v[172:175], v[180:183], v[122:125]
	v_mfma_f32_16x16x32_bf16 v[118:121], v[164:167], v[188:191], v[118:121]
	v_mfma_f32_16x16x32_bf16 v[114:117], v[172:175], v[188:191], v[114:117]
	v_mfma_f32_16x16x32_bf16 v[110:113], v[164:167], v[196:199], v[110:113]
	v_mfma_f32_16x16x32_bf16 v[106:109], v[172:175], v[196:199], v[106:109]
	v_mfma_f32_16x16x32_bf16 v[102:105], v[164:167], v[206:209], v[102:105]
	v_mfma_f32_16x16x32_bf16 v[98:101], v[172:175], v[206:209], v[98:101]
	v_mfma_f32_16x16x32_bf16 v[126:129], v[168:171], v[184:187], v[126:129]
	v_mfma_f32_16x16x32_bf16 v[122:125], v[176:179], v[184:187], v[122:125]
	v_mfma_f32_16x16x32_bf16 v[118:121], v[168:171], v[192:195], v[118:121]
	v_mfma_f32_16x16x32_bf16 v[114:117], v[176:179], v[192:195], v[114:117]
	v_mfma_f32_16x16x32_bf16 v[110:113], v[168:171], v[202:205], v[110:113]
	v_mfma_f32_16x16x32_bf16 v[106:109], v[176:179], v[202:205], v[106:109]
	v_mfma_f32_16x16x32_bf16 v[102:105], v[168:171], v[216:219], v[102:105]
	v_mfma_f32_16x16x32_bf16 v[98:101], v[176:179], v[216:219], v[98:101]
	s_setprio 0
	s_barrier
	s_mov_b64 s[2:3], 0x900180
	v_lshl_add_u64 v[222:223], v[212:213], 0, s[2:3]
	v_readfirstlane_b32 s2, v150
	s_mov_b32 m0, s2
	s_mov_b64 s[2:3], 0x920180
	ds_read_b128 v[228:231], v148
	ds_read_b128 v[232:235], v148 offset:1024
	ds_read_b128 v[236:239], v148 offset:2048
	ds_read_b128 v[240:243], v148 offset:3072
	global_load_lds_dwordx4 v[222:223], off
	v_lshl_add_u64 v[222:223], v[212:213], 0, s[2:3]
	v_readfirstlane_b32 s2, v151
	s_mov_b32 m0, s2
	s_nop 0
	global_load_lds_dwordx4 v[222:223], off
	s_barrier
	s_waitcnt lgkmcnt(0)
	s_setprio 1
	s_waitcnt lgkmcnt(0)
	v_mfma_f32_16x16x32_bf16 v[94:97], v[228:231], v[180:183], v[94:97]
	v_mfma_f32_16x16x32_bf16 v[90:93], v[236:239], v[180:183], v[90:93]
	v_mfma_f32_16x16x32_bf16 v[86:89], v[228:231], v[188:191], v[86:89]
	v_mfma_f32_16x16x32_bf16 v[82:85], v[236:239], v[188:191], v[82:85]
	v_mfma_f32_16x16x32_bf16 v[78:81], v[228:231], v[196:199], v[78:81]
	v_mfma_f32_16x16x32_bf16 v[74:77], v[236:239], v[196:199], v[74:77]
	v_mfma_f32_16x16x32_bf16 v[70:73], v[228:231], v[206:209], v[70:73]
	v_mfma_f32_16x16x32_bf16 v[66:69], v[236:239], v[206:209], v[66:69]
	v_mfma_f32_16x16x32_bf16 v[94:97], v[232:235], v[184:187], v[94:97]
	v_mfma_f32_16x16x32_bf16 v[90:93], v[240:243], v[184:187], v[90:93]
	v_mfma_f32_16x16x32_bf16 v[86:89], v[232:235], v[192:195], v[86:89]
	v_mfma_f32_16x16x32_bf16 v[82:85], v[240:243], v[192:195], v[82:85]
	v_mfma_f32_16x16x32_bf16 v[78:81], v[232:235], v[202:205], v[78:81]
	v_mfma_f32_16x16x32_bf16 v[74:77], v[240:243], v[202:205], v[74:77]
	v_mfma_f32_16x16x32_bf16 v[70:73], v[232:235], v[216:219], v[70:73]
	v_mfma_f32_16x16x32_bf16 v[66:69], v[240:243], v[216:219], v[66:69]
	s_setprio 0
	s_barrier
; #define STAGE_B(P, br, kt) do { const char* _gb = (const char*)(Bt + ((long)(br) * K + (long)(kt) * BK)); \
;     __builtin_amdgcn_global_load_lds((const unsigned*)(_gb + bofl0), (unsigned*)((char*)(P) + gtid_ * 16), 16, 0, 0); \
;     __builtin_amdgcn_global_load_lds((const unsigned*)(_gb + (long)K * 128 + bofl0), (unsigned*)((char*)(P) + gtid_ * 16 + 8192), 16, 0, 0); } while (0)
; #define LDA(dst, b, h) for (int m = 0; m < 4; ++m) for (int k = 0; k < 2; ++k) \
;     dst[m][k] = *reinterpret_cast<const bf16x8*>((char*)SA(b, h) + lds_byte(wr * 64 + m * 16 + fr, k * 32 + fq * 8))
; #define LDB(dst, b, h) for (int n = 0; n < 2; ++n) for (int k = 0; k < 2; ++k) \
;     dst[n][k] = *reinterpret_cast<const bf16x8*>((char*)SB(b, h) + lds_byte(wc * 32 + n * 16 + fr, k * 32 + fq * 8))
; #define MMA(ai, bj, At_, Bt_) do { __builtin_amdgcn_s_setprio(1); \
;     for (int m = 0; m < 4; ++m) for (int n = 0; n < 2; ++n) for (int k = 0; k < 2; ++k) \
;       acc[ai][bj][m][n] = __builtin_amdgcn_mfma_f32_16x16x32_bf16(At_[m][k], Bt_[n][k], acc[ai][bj][m][n], 0, 0, 0); \
;     __builtin_amdgcn_s_setprio(0); } while (0)
; #define WAIT_V(n) asm volatile("s_waitcnt vmcnt(" #n ")" ::: "memory")
; #define WAIT_L(n) asm volatile("s_waitcnt lgkmcnt(" #n ")" ::: "memory")
; #define BAR __builtin_amdgcn_s_barrier()
; #define SCHED __builtin_amdgcn_sched_barrier(0)
; template <int EPI>
; __device__ __forceinline__ void gemm_tile(const GemmArgs& g, int brow, int bcol, int parity, bool first, bool nvalid, int nbrow, int nbcol) {
;     ...
;     WAIT_V(6); BAR; MMA(1, 1, At, B1); BAR; SCHED;
;     LDB(B0, 1, 0); SCHED; LDA(At, 1, 0); STAGE_A(SA(0, 1), brow + HALF, t + 2);
;     WAIT_L(8); BAR; WAIT_L(0); MMA(0, 0, At, B0); BAR; SCHED;
;     LDB(B1, 1, 1); STAGE_B(SB(1, 0), bcol, t + 3);
;     BAR; WAIT_L(0); MMA(0, 1, At, B1); BAR; SCHED;
;     LDA(At, 1, 1); STAGE_A(SA(1, 0), brow, t + 3);
;     BAR; WAIT_L(0); MMA(1, 0, At, B0); BAR; SCHED;
;     STAGE_B(SB(1, 1), bcol + HALF, t + 3);
;     WAIT_V(6); BAR; MMA(1, 1, At, B1); BAR; SCHED;
;   }
;   { LDB(B0, 0, 0); LDA(At, 0, 0); STAGE_A(SA(1, 1), brow + HALF, nt - 1);
;     BAR; WAIT_L(0); MMA(0, 0, At, B0); BAR;
	v_readfirstlane_b32 s2, v152
	v_lshl_add_u64 v[222:223], v[210:211], 0, s[50:51]
	s_mov_b32 m0, s2
	v_readfirstlane_b32 s2, v153
	ds_read_b128 v[180:183], v147 offset:49152
	ds_read_b128 v[184:187], v147 offset:50176
	ds_read_b128 v[188:191], v146 offset:49152
	ds_read_b128 v[192:195], v146 offset:50176
	ds_read_b128 v[196:199], v145 offset:49152
	ds_read_b128 v[202:205], v145 offset:50176
	ds_read_b128 v[206:209], v144 offset:49152
	ds_read_b128 v[216:219], v144 offset:50176
	global_load_lds_dwordx4 v[222:223], off
	v_lshl_add_u64 v[210:211], v[210:211], 0, s[52:53]
	s_mov_b32 m0, s2
	s_nop 0
	global_load_lds_dwordx4 v[210:211], off
	s_barrier
	s_waitcnt lgkmcnt(0)
	s_setprio 1
	s_waitcnt lgkmcnt(0)
	v_mfma_f32_16x16x32_bf16 v[62:65], v[164:167], v[180:183], v[62:65]
	v_mfma_f32_16x16x32_bf16 v[58:61], v[172:175], v[180:183], v[58:61]
	v_mfma_f32_16x16x32_bf16 v[54:57], v[164:167], v[188:191], v[54:57]
	v_mfma_f32_16x16x32_bf16 v[50:53], v[172:175], v[188:191], v[50:53]
	v_mfma_f32_16x16x32_bf16 v[46:49], v[164:167], v[196:199], v[46:49]
	v_mfma_f32_16x16x32_bf16 v[42:45], v[172:175], v[196:199], v[42:45]
	v_mfma_f32_16x16x32_bf16 v[38:41], v[164:167], v[206:209], v[38:41]
	v_mfma_f32_16x16x32_bf16 v[34:37], v[172:175], v[206:209], v[34:37]
	v_mfma_f32_16x16x32_bf16 v[62:65], v[168:171], v[184:187], v[62:65]
	v_mfma_f32_16x16x32_bf16 v[58:61], v[176:179], v[184:187], v[58:61]
	v_mfma_f32_16x16x32_bf16 v[54:57], v[168:171], v[192:195], v[54:57]
	v_mfma_f32_16x16x32_bf16 v[50:53], v[176:179], v[192:195], v[50:53]
	v_mfma_f32_16x16x32_bf16 v[46:49], v[168:171], v[202:205], v[46:49]
	v_mfma_f32_16x16x32_bf16 v[42:45], v[176:179], v[202:205], v[42:45]
	v_mfma_f32_16x16x32_bf16 v[38:41], v[168:171], v[216:219], v[38:41]
	v_mfma_f32_16x16x32_bf16 v[34:37], v[176:179], v[216:219], v[34:37]
	s_setprio 0
	s_barrier
	s_mov_b64 s[2:3], 0x940180
	v_lshl_add_u64 v[164:165], v[212:213], 0, s[2:3]
	v_readfirstlane_b32 s2, v155
	s_mov_b32 m0, s2
	s_mov_b64 s[2:3], 0x960180
	global_load_lds_dwordx4 v[164:165], off
	v_lshl_add_u64 v[164:165], v[212:213], 0, s[2:3]
	v_readfirstlane_b32 s2, v156
	s_mov_b32 m0, s2
	s_nop 0
	global_load_lds_dwordx4 v[164:165], off
	s_waitcnt vmcnt(6)
	s_barrier
	s_setprio 1
	v_mfma_f32_16x16x32_bf16 v[30:33], v[228:231], v[180:183], v[30:33]
	v_mfma_f32_16x16x32_bf16 v[26:29], v[236:239], v[180:183], v[26:29]
	v_mfma_f32_16x16x32_bf16 v[22:25], v[228:231], v[188:191], v[22:25]
	v_mfma_f32_16x16x32_bf16 v[18:21], v[236:239], v[188:191], v[18:21]
	v_mfma_f32_16x16x32_bf16 v[14:17], v[228:231], v[196:199], v[14:17]
	v_mfma_f32_16x16x32_bf16 v[10:13], v[236:239], v[196:199], v[10:13]
	v_mfma_f32_16x16x32_bf16 v[6:9], v[228:231], v[206:209], v[6:9]
	v_mfma_f32_16x16x32_bf16 v[2:5], v[236:239], v[206:209], v[2:5]
	v_mfma_f32_16x16x32_bf16 v[30:33], v[232:235], v[184:187], v[30:33]
	v_mfma_f32_16x16x32_bf16 v[26:29], v[240:243], v[184:187], v[26:29]
	v_mfma_f32_16x16x32_bf16 v[22:25], v[232:235], v[192:195], v[22:25]
	v_mfma_f32_16x16x32_bf16 v[18:21], v[240:243], v[192:195], v[18:21]
	v_mfma_f32_16x16x32_bf16 v[14:17], v[232:235], v[202:205], v[14:17]
	v_mfma_f32_16x16x32_bf16 v[10:13], v[240:243], v[202:205], v[10:13]
	v_mfma_f32_16x16x32_bf16 v[6:9], v[232:235], v[216:219], v[6:9]
	v_mfma_f32_16x16x32_bf16 v[2:5], v[240:243], v[216:219], v[2:5]
	s_setprio 0
	s_barrier
	s_add_i32 s15, s15, 2
	s_add_u32 s0, s0, 0x100
	s_addc_u32 s1, s1, 0
	s_add_u32 s12, s12, 0x100
	s_addc_u32 s13, s13, 0
	s_cmp_lt_u32 s15, 12
	s_cbranch_scc1 .LBB0_90
	s_or_b32 s0, s38, 0x80
	s_ashr_i32 s1, s0, 31
	s_lshl_b64 s[0:1], s[0:1], 11
	s_add_u32 s0, s80, s0
	s_addc_u32 s1, s81, s1
	v_lshl_add_u64 v[130:131], s[0:1], 0, v[0:1]
	s_mov_b64 s[0:1], 0x780
	ds_read_b128 v[150:153], v157
	ds_read_b128 v[164:167], v157 offset:1024
	ds_read_b128 v[168:171], v157 offset:2048
	ds_read_b128 v[172:175], v157 offset:3072
	ds_read_b128 v[176:179], v147
	ds_read_b128 v[180:183], v147 offset:1024
	ds_read_b128 v[184:187], v146
	ds_read_b128 v[188:191], v146 offset:1024
	ds_read_b128 v[192:195], v145
	ds_read_b128 v[196:199], v145 offset:1024
	ds_read_b128 v[202:205], v144
	ds_read_b128 v[206:209], v144 offset:1024
	v_lshl_add_u64 v[156:157], v[130:131], 0, s[0:1]
	v_readfirstlane_b32 s0, v161
	s_mov_b32 m0, s0
	s_mov_b64 s[0:1], 0x20780
	v_lshl_add_u64 v[130:131], v[130:131], 0, s[0:1]
	v_readfirstlane_b32 s0, v162
	global_load_lds_dwordx4 v[156:157], off
	s_mov_b32 m0, s0
	s_nop 0
	global_load_lds_dwordx4 v[130:131], off
	s_barrier
	s_waitcnt lgkmcnt(0)
	s_setprio 1
	s_waitcnt lgkmcnt(0)
	v_mfma_f32_16x16x32_bf16 v[126:129], v[150:153], v[176:179], v[126:129]
	v_mfma_f32_16x16x32_bf16 v[118:121], v[150:153], v[184:187], v[118:121]
	v_mfma_f32_16x16x32_bf16 v[110:113], v[150:153], v[192:195], v[110:113]
	v_mfma_f32_16x16x32_bf16 v[102:105], v[150:153], v[202:205], v[102:105]
	v_mfma_f32_16x16x32_bf16 v[126:129], v[164:167], v[180:183], v[126:129]
	v_mfma_f32_16x16x32_bf16 v[122:125], v[168:171], v[176:179], v[122:125]
	v_mfma_f32_16x16x32_bf16 v[118:121], v[164:167], v[188:191], v[118:121]
	v_mfma_f32_16x16x32_bf16 v[114:117], v[168:171], v[184:187], v[114:117]
	v_mfma_f32_16x16x32_bf16 v[110:113], v[164:167], v[196:199], v[110:113]
	v_mfma_f32_16x16x32_bf16 v[106:109], v[168:171], v[192:195], v[106:109]
	v_mfma_f32_16x16x32_bf16 v[102:105], v[164:167], v[206:209], v[102:105]
	v_mfma_f32_16x16x32_bf16 v[98:101], v[168:171], v[202:205], v[98:101]
	v_mfma_f32_16x16x32_bf16 v[216:219], v[172:175], v[180:183], v[122:125]
	v_mfma_f32_16x16x32_bf16 v[228:231], v[172:175], v[188:191], v[114:117]
	v_mfma_f32_16x16x32_bf16 v[232:235], v[172:175], v[196:199], v[106:109]
	v_mfma_f32_16x16x32_bf16 v[236:239], v[172:175], v[206:209], v[98:101]
	s_setprio 0
	s_barrier
; #define LDA(dst, b, h) for (int m = 0; m < 4; ++m) for (int k = 0; k < 2; ++k) \
;     dst[m][k] = *reinterpret_cast<const bf16x8*>((char*)SA(b, h) + lds_byte(wr * 64 + m * 16 + fr, k * 32 + fq * 8))
; #define LDB(dst, b, h) for (int n = 0; n < 2; ++n) for (int k = 0; k < 2; ++k) \
;     dst[n][k] = *reinterpret_cast<const bf16x8*>((char*)SB(b, h) + lds_byte(wc * 32 + n * 16 + fr, k * 32 + fq * 8))
; #define MMA(ai, bj, At_, Bt_) do { __builtin_amdgcn_s_setprio(1); \
;     for (int m = 0; m < 4; ++m) for (int n = 0; n < 2; ++n) for (int k = 0; k < 2; ++k) \
;       acc[ai][bj][m][n] = __builtin_amdgcn_mfma_f32_16x16x32_bf16(At_[m][k], Bt_[n][k], acc[ai][bj][m][n], 0, 0, 0); \
;     __builtin_amdgcn_s_setprio(0); } while (0)
; #define WAIT_V(n) asm volatile("s_waitcnt vmcnt(" #n ")" ::: "memory")
; #define WAIT_L(n) asm volatile("s_waitcnt lgkmcnt(" #n ")" ::: "memory")
; #define BAR __builtin_amdgcn_s_barrier()
; #define SCHED __builtin_amdgcn_sched_barrier(0)
; template <int EPI>
; __device__ __forceinline__ void gemm_tile(const GemmArgs& g, int brow, int bcol, int parity, bool first, bool nvalid, int nbrow, int nbcol) {
;     ...
;   { LDB(B0, 0, 0); LDA(At, 0, 0); STAGE_A(SA(1, 1), brow + HALF, nt - 1);
;     BAR; WAIT_L(0); MMA(0, 0, At, B0); BAR;
;     LDB(B1, 0, 1); BAR; WAIT_L(0); MMA(0, 1, At, B1); BAR; SCHED;
;     LDA(At, 0, 1); WAIT_V(4); BAR; WAIT_L(0); MMA(1, 0, At, B0); MMA(1, 1, At, B1); BAR; }
;   { LDB(B0, 1, 0); LDA(At, 1, 0); WAIT_V(2); BAR; WAIT_L(0); MMA(0, 0, At, B0); BAR;
;     LDB(B1, 1, 1); WAIT_V(0); BAR; WAIT_L(0); MMA(0, 1, At, B1); BAR; SCHED;
	s_nop 1
	ds_read_b128 v[98:101], v154
	ds_read_b128 v[106:109], v154 offset:1024
	ds_read_b128 v[114:117], v154 offset:2048
	ds_read_b128 v[122:125], v154 offset:3072
	s_barrier
	s_waitcnt lgkmcnt(0)
	s_setprio 1
	s_waitcnt lgkmcnt(0)
	v_mfma_f32_16x16x32_bf16 v[94:97], v[98:101], v[176:179], v[94:97]
	v_mfma_f32_16x16x32_bf16 v[86:89], v[98:101], v[184:187], v[86:89]
	v_mfma_f32_16x16x32_bf16 v[78:81], v[98:101], v[192:195], v[78:81]
	v_mfma_f32_16x16x32_bf16 v[70:73], v[98:101], v[202:205], v[70:73]
	v_mfma_f32_16x16x32_bf16 v[94:97], v[106:109], v[180:183], v[94:97]
	v_mfma_f32_16x16x32_bf16 v[90:93], v[114:117], v[176:179], v[90:93]
	v_mfma_f32_16x16x32_bf16 v[86:89], v[106:109], v[188:191], v[86:89]
	v_mfma_f32_16x16x32_bf16 v[82:85], v[114:117], v[184:187], v[82:85]
	v_mfma_f32_16x16x32_bf16 v[78:81], v[106:109], v[196:199], v[78:81]
	v_mfma_f32_16x16x32_bf16 v[74:77], v[114:117], v[192:195], v[74:77]
	v_mfma_f32_16x16x32_bf16 v[70:73], v[106:109], v[206:209], v[70:73]
	v_mfma_f32_16x16x32_bf16 v[66:69], v[114:117], v[202:205], v[66:69]
	v_mfma_f32_16x16x32_bf16 v[154:157], v[122:125], v[180:183], v[90:93]
	v_mfma_f32_16x16x32_bf16 v[176:179], v[122:125], v[188:191], v[82:85]
	v_mfma_f32_16x16x32_bf16 v[180:183], v[122:125], v[196:199], v[74:77]
	v_mfma_f32_16x16x32_bf16 v[184:187], v[122:125], v[206:209], v[66:69]
	s_setprio 0
	s_barrier
	s_nop 1
	ds_read_b128 v[66:69], v147 offset:16384
	ds_read_b128 v[74:77], v147 offset:17408
	ds_read_b128 v[82:85], v146 offset:16384
	ds_read_b128 v[90:93], v146 offset:17408
	ds_read_b128 v[188:191], v145 offset:16384
	ds_read_b128 v[192:195], v145 offset:17408
	ds_read_b128 v[196:199], v144 offset:16384
	ds_read_b128 v[202:205], v144 offset:17408
	s_waitcnt vmcnt(4)
	s_barrier
	s_waitcnt lgkmcnt(0)
	s_setprio 1
	s_waitcnt lgkmcnt(0)
	v_mfma_f32_16x16x32_bf16 v[62:65], v[150:153], v[66:69], v[62:65]
	v_mfma_f32_16x16x32_bf16 v[54:57], v[150:153], v[82:85], v[54:57]
	v_mfma_f32_16x16x32_bf16 v[46:49], v[150:153], v[188:191], v[46:49]
	v_mfma_f32_16x16x32_bf16 v[38:41], v[150:153], v[196:199], v[38:41]
	v_mfma_f32_16x16x32_bf16 v[62:65], v[164:167], v[74:77], v[62:65]
	v_mfma_f32_16x16x32_bf16 v[58:61], v[168:171], v[66:69], v[58:61]
	v_mfma_f32_16x16x32_bf16 v[54:57], v[164:167], v[90:93], v[54:57]
	v_mfma_f32_16x16x32_bf16 v[50:53], v[168:171], v[82:85], v[50:53]
	v_mfma_f32_16x16x32_bf16 v[46:49], v[164:167], v[192:195], v[46:49]
	v_mfma_f32_16x16x32_bf16 v[42:45], v[168:171], v[188:191], v[42:45]
	v_mfma_f32_16x16x32_bf16 v[38:41], v[164:167], v[202:205], v[38:41]
	v_mfma_f32_16x16x32_bf16 v[34:37], v[168:171], v[196:199], v[34:37]
	v_mfma_f32_16x16x32_bf16 v[206:209], v[172:175], v[74:77], v[58:61]
	v_mfma_f32_16x16x32_bf16 v[240:243], v[172:175], v[90:93], v[50:53]
	v_mfma_f32_16x16x32_bf16 v[244:247], v[172:175], v[192:195], v[42:45]
	v_mfma_f32_16x16x32_bf16 v[150:153], v[172:175], v[202:205], v[34:37]
	s_setprio 0
	s_setprio 1
	v_mfma_f32_16x16x32_bf16 v[30:33], v[98:101], v[66:69], v[30:33]
	v_mfma_f32_16x16x32_bf16 v[22:25], v[98:101], v[82:85], v[22:25]
	v_mfma_f32_16x16x32_bf16 v[14:17], v[98:101], v[188:191], v[14:17]
	v_mfma_f32_16x16x32_bf16 v[6:9], v[98:101], v[196:199], v[6:9]
	v_mfma_f32_16x16x32_bf16 v[30:33], v[106:109], v[74:77], v[30:33]
	v_mfma_f32_16x16x32_bf16 v[26:29], v[114:117], v[66:69], v[26:29]
	v_mfma_f32_16x16x32_bf16 v[22:25], v[106:109], v[90:93], v[22:25]
	v_mfma_f32_16x16x32_bf16 v[18:21], v[114:117], v[82:85], v[18:21]
	v_mfma_f32_16x16x32_bf16 v[14:17], v[106:109], v[192:195], v[14:17]
	v_mfma_f32_16x16x32_bf16 v[10:13], v[114:117], v[188:191], v[10:13]
	v_mfma_f32_16x16x32_bf16 v[6:9], v[106:109], v[202:205], v[6:9]
	v_mfma_f32_16x16x32_bf16 v[2:5], v[114:117], v[196:199], v[2:5]
	v_mfma_f32_16x16x32_bf16 v[162:165], v[122:125], v[74:77], v[26:29]
	v_mfma_f32_16x16x32_bf16 v[166:169], v[122:125], v[90:93], v[18:21]
	v_mfma_f32_16x16x32_bf16 v[170:173], v[122:125], v[192:195], v[10:13]
	v_mfma_f32_16x16x32_bf16 v[188:191], v[122:125], v[202:205], v[2:5]
	s_setprio 0
	s_barrier
	s_nop 1
	ds_read_b128 v[2:5], v149
	ds_read_b128 v[10:13], v149 offset:1024
	ds_read_b128 v[18:21], v149 offset:2048
	ds_read_b128 v[26:29], v149 offset:3072
	ds_read_b128 v[34:37], v147 offset:32768
	ds_read_b128 v[42:45], v147 offset:33792
	ds_read_b128 v[50:53], v146 offset:32768
	ds_read_b128 v[58:61], v146 offset:33792
	ds_read_b128 v[66:69], v145 offset:32768
	ds_read_b128 v[192:195], v145 offset:33792
	ds_read_b128 v[196:199], v144 offset:32768
	ds_read_b128 v[202:205], v144 offset:33792
	s_waitcnt vmcnt(2)
	s_barrier
; #define LDA(dst, b, h) for (int m = 0; m < 4; ++m) for (int k = 0; k < 2; ++k) \
;     dst[m][k] = *reinterpret_cast<const bf16x8*>((char*)SA(b, h) + lds_byte(wr * 64 + m * 16 + fr, k * 32 + fq * 8))
; #define LDB(dst, b, h) for (int n = 0; n < 2; ++n) for (int k = 0; k < 2; ++k) \
;     dst[n][k] = *reinterpret_cast<const bf16x8*>((char*)SB(b, h) + lds_byte(wc * 32 + n * 16 + fr, k * 32 + fq * 8))
; #define MMA(ai, bj, At_, Bt_) do { __builtin_amdgcn_s_setprio(1); \
;     for (int m = 0; m < 4; ++m) for (int n = 0; n < 2; ++n) for (int k = 0; k < 2; ++k) \
;       acc[ai][bj][m][n] = __builtin_amdgcn_mfma_f32_16x16x32_bf16(At_[m][k], Bt_[n][k], acc[ai][bj][m][n], 0, 0, 0); \
;     __builtin_amdgcn_s_setprio(0); } while (0)
; #define WAIT_V(n) asm volatile("s_waitcnt vmcnt(" #n ")" ::: "memory")
; #define WAIT_L(n) asm volatile("s_waitcnt lgkmcnt(" #n ")" ::: "memory")
; #define BAR __builtin_amdgcn_s_barrier()
; #define SCHED __builtin_amdgcn_sched_barrier(0)
; template <int EPI>
; __device__ __forceinline__ void gemm_tile(const GemmArgs& g, int brow, int bcol, int parity, bool first, bool nvalid, int nbrow, int nbcol) {
;     ...
;     LDA(At, 0, 1); WAIT_V(4); BAR; WAIT_L(0); MMA(1, 0, At, B0); MMA(1, 1, At, B1); BAR; }
;   { LDB(B0, 1, 0); LDA(At, 1, 0); WAIT_V(2); BAR; WAIT_L(0); MMA(0, 0, At, B0); BAR;
;     LDB(B1, 1, 1); WAIT_V(0); BAR; WAIT_L(0); MMA(0, 1, At, B1); BAR; SCHED;
;     LDA(At, 1, 1); BAR; WAIT_L(0); MMA(1, 0, At, B0); MMA(1, 1, At, B1); BAR; }
;   if (wr == 0) BAR;
	s_waitcnt lgkmcnt(0)
	s_setprio 1
	s_waitcnt lgkmcnt(0)
	v_mfma_f32_16x16x32_bf16 v[74:77], v[2:5], v[34:37], v[126:129]
	v_mfma_f32_16x16x32_bf16 v[122:125], v[10:13], v[42:45], v[74:77]
	v_mfma_f32_16x16x32_bf16 v[74:77], v[18:21], v[34:37], v[216:219]
	v_mfma_f32_16x16x32_bf16 v[126:129], v[26:29], v[42:45], v[74:77]
	v_mfma_f32_16x16x32_bf16 v[74:77], v[2:5], v[50:53], v[118:121]
	v_mfma_f32_16x16x32_bf16 v[114:117], v[10:13], v[58:61], v[74:77]
	v_mfma_f32_16x16x32_bf16 v[74:77], v[18:21], v[50:53], v[228:231]
	v_mfma_f32_16x16x32_bf16 v[118:121], v[26:29], v[58:61], v[74:77]
	v_mfma_f32_16x16x32_bf16 v[74:77], v[2:5], v[66:69], v[110:113]
	v_mfma_f32_16x16x32_bf16 v[106:109], v[10:13], v[192:195], v[74:77]
	v_mfma_f32_16x16x32_bf16 v[74:77], v[18:21], v[66:69], v[232:235]
	v_mfma_f32_16x16x32_bf16 v[110:113], v[26:29], v[192:195], v[74:77]
	v_mfma_f32_16x16x32_bf16 v[74:77], v[2:5], v[196:199], v[102:105]
	v_mfma_f32_16x16x32_bf16 v[98:101], v[10:13], v[202:205], v[74:77]
	v_mfma_f32_16x16x32_bf16 v[74:77], v[18:21], v[196:199], v[236:239]
	v_mfma_f32_16x16x32_bf16 v[102:105], v[26:29], v[202:205], v[74:77]
	s_setprio 0
	s_barrier
	ds_read_b128 v[216:219], v148
	ds_read_b128 v[228:231], v148 offset:1024
	ds_read_b128 v[232:235], v148 offset:2048
	ds_read_b128 v[236:239], v148 offset:3072
	s_waitcnt vmcnt(0)
	s_barrier
	s_waitcnt lgkmcnt(0)
	s_setprio 1
	s_waitcnt lgkmcnt(0)
	v_mfma_f32_16x16x32_bf16 v[74:77], v[216:219], v[34:37], v[94:97]
	v_mfma_f32_16x16x32_bf16 v[34:37], v[232:235], v[34:37], v[154:157]
	v_mfma_f32_16x16x32_bf16 v[94:97], v[236:239], v[42:45], v[34:37]
	v_mfma_f32_16x16x32_bf16 v[34:37], v[216:219], v[50:53], v[86:89]
	v_mfma_f32_16x16x32_bf16 v[82:85], v[228:231], v[58:61], v[34:37]
	v_mfma_f32_16x16x32_bf16 v[34:37], v[232:235], v[50:53], v[176:179]
	v_mfma_f32_16x16x32_bf16 v[86:89], v[236:239], v[58:61], v[34:37]
	v_mfma_f32_16x16x32_bf16 v[34:37], v[216:219], v[66:69], v[78:81]
	v_mfma_f32_16x16x32_bf16 v[90:93], v[228:231], v[42:45], v[74:77]
	v_mfma_f32_16x16x32_bf16 v[74:77], v[228:231], v[192:195], v[34:37]
	v_mfma_f32_16x16x32_bf16 v[34:37], v[232:235], v[66:69], v[180:183]
	v_mfma_f32_16x16x32_bf16 v[78:81], v[236:239], v[192:195], v[34:37]
	v_mfma_f32_16x16x32_bf16 v[34:37], v[216:219], v[196:199], v[70:73]
	v_mfma_f32_16x16x32_bf16 v[66:69], v[228:231], v[202:205], v[34:37]
	v_mfma_f32_16x16x32_bf16 v[34:37], v[232:235], v[196:199], v[184:187]
	v_mfma_f32_16x16x32_bf16 v[70:73], v[236:239], v[202:205], v[34:37]
	s_setprio 0
	s_barrier
	ds_read_b128 v[154:157], v147 offset:49152
	ds_read_b128 v[174:177], v147 offset:50176
	ds_read_b128 v[178:181], v146 offset:49152
	ds_read_b128 v[146:149], v146 offset:50176
	ds_read_b128 v[182:185], v145 offset:49152
	ds_read_b128 v[192:195], v145 offset:50176
	ds_read_b128 v[196:199], v144 offset:49152
	ds_read_b128 v[202:205], v144 offset:50176
	s_barrier
	s_waitcnt lgkmcnt(0)
	s_setprio 1
	s_waitcnt lgkmcnt(0)
	v_mfma_f32_16x16x32_bf16 v[34:37], v[2:5], v[154:157], v[62:65]
	v_mfma_f32_16x16x32_bf16 v[58:61], v[10:13], v[174:177], v[34:37]
	v_mfma_f32_16x16x32_bf16 v[34:37], v[18:21], v[154:157], v[206:209]
	v_mfma_f32_16x16x32_bf16 v[62:65], v[26:29], v[174:177], v[34:37]
	v_mfma_f32_16x16x32_bf16 v[34:37], v[2:5], v[178:181], v[54:57]
	v_mfma_f32_16x16x32_bf16 v[50:53], v[10:13], v[146:149], v[34:37]
	v_mfma_f32_16x16x32_bf16 v[34:37], v[18:21], v[178:181], v[240:243]
	v_mfma_f32_16x16x32_bf16 v[54:57], v[26:29], v[146:149], v[34:37]
	v_mfma_f32_16x16x32_bf16 v[34:37], v[2:5], v[182:185], v[46:49]
	v_mfma_f32_16x16x32_bf16 v[42:45], v[10:13], v[192:195], v[34:37]
	v_mfma_f32_16x16x32_bf16 v[34:37], v[18:21], v[182:185], v[244:247]
	v_mfma_f32_16x16x32_bf16 v[2:5], v[2:5], v[196:199], v[38:41]
	v_mfma_f32_16x16x32_bf16 v[46:49], v[26:29], v[192:195], v[34:37]
	v_mfma_f32_16x16x32_bf16 v[34:37], v[10:13], v[202:205], v[2:5]
	v_mfma_f32_16x16x32_bf16 v[2:5], v[18:21], v[196:199], v[150:153]
	v_mfma_f32_16x16x32_bf16 v[38:41], v[26:29], v[202:205], v[2:5]
	s_setprio 0
	s_setprio 1
	v_mfma_f32_16x16x32_bf16 v[2:5], v[216:219], v[154:157], v[30:33]
	v_mfma_f32_16x16x32_bf16 v[26:29], v[228:231], v[174:177], v[2:5]
	v_mfma_f32_16x16x32_bf16 v[2:5], v[232:235], v[154:157], v[162:165]
	v_mfma_f32_16x16x32_bf16 v[30:33], v[236:239], v[174:177], v[2:5]
	v_mfma_f32_16x16x32_bf16 v[2:5], v[216:219], v[178:181], v[22:25]
	v_mfma_f32_16x16x32_bf16 v[18:21], v[228:231], v[146:149], v[2:5]
	v_mfma_f32_16x16x32_bf16 v[2:5], v[232:235], v[178:181], v[166:169]
	v_mfma_f32_16x16x32_bf16 v[22:25], v[236:239], v[146:149], v[2:5]
	v_mfma_f32_16x16x32_bf16 v[2:5], v[216:219], v[182:185], v[14:17]
	v_mfma_f32_16x16x32_bf16 v[10:13], v[228:231], v[192:195], v[2:5]
	v_mfma_f32_16x16x32_bf16 v[2:5], v[232:235], v[182:185], v[170:173]
	v_mfma_f32_16x16x32_bf16 v[14:17], v[236:239], v[192:195], v[2:5]
	v_mfma_f32_16x16x32_bf16 v[2:5], v[216:219], v[196:199], v[6:9]
	v_mfma_f32_16x16x32_bf16 v[6:9], v[232:235], v[196:199], v[188:191]
	v_mfma_f32_16x16x32_bf16 v[2:5], v[228:231], v[202:205], v[2:5]
	v_mfma_f32_16x16x32_bf16 v[6:9], v[236:239], v[202:205], v[6:9]
	s_setprio 0
	s_movk_i32 s0, 0x100
	v_cmp_gt_u32_e32 vcc, s0, v138
	s_barrier
	s_and_saveexec_b64 s[0:1], vcc
	s_cbranch_execz .LBB0_93
	s_barrier
